# no-gain weight transposes (w_out/w_branch, both call sites): 4 serialized tile loads per item issued together
# speedup vs baseline: 1.0052x; 1.0052x over previous
; DI uint32_t pack2(float a, float b) { f2_t v = {a, b}; bf2_t r = __builtin_convertvector(v, bf2_t); return __builtin_bit_cast(uint32_t, r); }
; DI int opaque_tid() { int t = threadIdx.x; asm volatile("" : "+v"(t)); return t; }
; template <bool MAP>
; DI void transpose_tile(const float* __restrict__ src, int N, int K, int Nvalid, const float* __restrict__ g,
;                        u16* __restrict__ dst, int ldd, int k0, int n0, float* sT) {
;   const int tid = opaque_tid();
;   const int cg = (tid & 15) * 4, kq = tid >> 4;
;   const int sc = MAP ? src_col(n0 + cg) : ((n0 + cg < Nvalid) ? n0 + cg : -1);
; #pragma unroll
;   for (int i = 0; i < 4; ++i) {
;     const int kk = i * 16 + kq;
;     float4 v = make_float4(0.f, 0.f, 0.f, 0.f);
;     if (sc >= 0) {
;       v = *(const float4*)(src + (size_t)(k0 + kk) * N + sc);
;       if (g) { const float gg = g[k0 + kk]; v.x *= gg; v.y *= gg; v.z *= gg; v.w *= gg; }
;     }
;     float* d = sT + kk * 65 + cg;
;     d[0] = v.x; d[1] = v.y; d[2] = v.z; d[3] = v.w;
;   }
;   __syncthreads();
;   const int n = tid >> 2, kc = (tid & 3) * 16;
;   uint32_t o[8];
; #pragma unroll
;   for (int j = 0; j < 8; ++j) o[j] = pack2(sT[(kc + 2 * j) * 65 + n], sT[(kc + 2 * j + 1) * 65 + n]);
;   uint4* d = (uint4*)(dst + (size_t)(n0 + n) * ldd + k0 + kc);
;   d[0] = make_uint4(o[0], o[1], o[2], o[3]);
;   d[1] = make_uint4(o[4], o[5], o[6], o[7]);
;   __syncthreads();
; DI void convert_item(const Params& p, int layer, int item, float* sT) {
;     ...
;   {
;     int kt = item & 15, nt = item >> 4;
;     transpose_tile<false>(p.w_out + (size_t)layer * 1024 * 1024, 1024, 1024, 1024, nullptr, (u16*)(wset + OFF_WT_OUT), LDX, kt * 64, nt * 64, sT);
;   }
.LBB0_287:
	s_cmpk_gt_i32 s59, 0xfff
	s_mov_b64 s[0:1], -1
	s_cbranch_scc0 .LBB0_358
	s_cmpk_gt_u32 s59, 0x13ff
	s_cbranch_scc0 .LBB0_348
	s_add_i32 s5, s59, 0xffffec00
	s_cmpk_gt_u32 s5, 0x75f
	s_cbranch_scc0 .LBB0_319
	s_cmpk_gt_u32 s5, 0x78f
	s_cbranch_scc0 .LBB0_308
	s_cmpk_gt_u32 s5, 0x7af
	s_cbranch_scc0 .LBB0_297
	s_cmpk_gt_u32 s5, 0x92f
	s_cbranch_scc0 .LBB0_294
	v_mov_b32_e32 v10, v128
	s_and_b32 s0, s58, 0x3c0
	s_and_b32 s1, s31, 0x7fffffc0
	s_addk_i32 s1, 0xdb40
	v_lshlrev_b32_e32 v0, 2, v10
	v_ashrrev_i32_e32 v7, 4, v10
	v_and_b32_e32 v6, 60, v0
	v_readlane_b32 s12, v254, 39
	v_add_u32_e32 v8, s0, v7
	v_or_b32_e32 v2, s1, v6
	v_readlane_b32 s13, v254, 40
	v_ashrrev_i32_e32 v9, 31, v8
	s_waitcnt lgkmcnt(0)
	v_lshlrev_b64 v[4:5], 12, v[8:9]
	v_lshl_add_u64 v[0:1], v[2:3], 2, s[12:13]
	s_movk_i32 s12, 0x104
	v_lshl_add_u64 v[4:5], v[0:1], 0, v[4:5]
	v_mul_lo_u32 v2, v7, s12
	v_lshl_add_u32 v2, v6, 2, v2
	v_add_co_u32_e32 v108, vcc, 0x10000, v4
	s_nop 1
	v_addc_co_u32_e32 v109, vcc, 0, v5, vcc
	v_add_co_u32_e32 v110, vcc, 0x20000, v4
	s_nop 1
	v_addc_co_u32_e32 v111, vcc, 0, v5, vcc
	v_add_co_u32_e32 v112, vcc, 0x30000, v4
	s_nop 1
	v_addc_co_u32_e32 v113, vcc, 0, v5, vcc
	global_load_dwordx4 v[4:7], v[4:5], off
	global_load_dwordx4 v[96:99], v[108:109], off
	global_load_dwordx4 v[100:103], v[110:111], off
	global_load_dwordx4 v[104:107], v[112:113], off
	v_add_u32_e32 v9, 0x1040, v2
	v_readlane_b32 s12, v254, 41
	v_readlane_b32 s13, v254, 42
	s_lshl_b32 s16, s0, 1
	s_waitcnt vmcnt(0)
	ds_write2_b32 v2, v4, v5 offset1:1
	ds_write2_b32 v2, v6, v7 offset0:2 offset1:3
	v_add_u32_e32 v4, 16, v8
	v_ashrrev_i32_e32 v5, 31, v4
	v_lshlrev_b64 v[4:5], 12, v[4:5]
	v_lshl_add_u64 v[4:5], v[0:1], 0, v[4:5]
	v_mov_b64_e32 v[4:5], v[96:97]
	v_mov_b64_e32 v[6:7], v[98:99]
	s_waitcnt vmcnt(0)
	ds_write2_b32 v9, v4, v5 offset1:1
	v_add_u32_e32 v4, 0x1048, v2
	ds_write2_b32 v4, v6, v7 offset1:1
	v_add_u32_e32 v4, 32, v8
	v_ashrrev_i32_e32 v5, 31, v4
	v_lshlrev_b64 v[4:5], 12, v[4:5]
	v_lshl_add_u64 v[4:5], v[0:1], 0, v[4:5]
	v_mov_b64_e32 v[4:5], v[100:101]
	v_mov_b64_e32 v[6:7], v[102:103]
	v_add_u32_e32 v9, 0x2080, v2
	s_waitcnt vmcnt(0)
	ds_write2_b32 v9, v4, v5 offset1:1
	v_add_u32_e32 v4, 0x2088, v2
	ds_write2_b32 v4, v6, v7 offset1:1
	v_add_u32_e32 v4, 48, v8
	v_ashrrev_i32_e32 v5, 31, v4
	v_lshlrev_b64 v[4:5], 12, v[4:5]
	v_lshl_add_u64 v[0:1], v[0:1], 0, v[4:5]
	v_mov_b64_e32 v[4:5], v[104:105]
	v_mov_b64_e32 v[6:7], v[106:107]
	v_add_u32_e32 v0, 0x30c8, v2
	v_add_u32_e32 v8, 0x30c0, v2
	v_ashrrev_i32_e32 v2, 2, v10
	v_add_u32_e32 v2, s1, v2
	s_mov_b64 s[0:1], 0
	s_waitcnt vmcnt(0)
	ds_write2_b32 v0, v6, v7 offset1:1
	v_lshlrev_b32_e32 v0, 4, v10
	v_and_b32_e32 v12, 48, v0
	v_and_b32_e32 v0, -4, v10
	v_mul_u32_u24_e32 v1, 0x41, v12
	v_lshl_add_u32 v10, v1, 2, v0
	ds_write2_b32 v8, v4, v5 offset1:1
	s_waitcnt lgkmcnt(0)
	s_barrier
	ds_read2_b32 v[0:1], v10 offset1:65
	v_add_u32_e32 v7, 0x400, v10
	v_add_u32_e32 v9, 0x800, v10
	v_add_u32_e32 v11, 0xc00, v10
	s_waitcnt lgkmcnt(0)
	v_cvt_pk_bf16_f32 v4, v0, v1
	ds_read2_b32 v[0:1], v10 offset0:130 offset1:195
	s_waitcnt lgkmcnt(0)
	v_cvt_pk_bf16_f32 v5, v0, v1
	ds_read2_b32 v[0:1], v7 offset0:4 offset1:69
	s_waitcnt lgkmcnt(0)
	v_cvt_pk_bf16_f32 v6, v0, v1
	ds_read2_b32 v[0:1], v7 offset0:134 offset1:199
	s_waitcnt lgkmcnt(0)
	v_cvt_pk_bf16_f32 v7, v0, v1
	ds_read2_b32 v[0:1], v9 offset0:8 offset1:73
	s_waitcnt lgkmcnt(0)
	v_cvt_pk_bf16_f32 v8, v0, v1
	ds_read2_b32 v[0:1], v9 offset0:138 offset1:203
	s_waitcnt lgkmcnt(0)
	v_cvt_pk_bf16_f32 v9, v0, v1
	ds_read2_b32 v[0:1], v11 offset0:12 offset1:77
	s_waitcnt lgkmcnt(0)
	v_cvt_pk_bf16_f32 v10, v0, v1
	ds_read2_b32 v[0:1], v11 offset0:142 offset1:207
	s_waitcnt lgkmcnt(0)
	v_cvt_pk_bf16_f32 v11, v0, v1
	v_mov_b64_e32 v[0:1], s[12:13]
	v_mad_i64_i32 v[0:1], s[12:13], v2, s24, v[0:1]
	v_lshl_add_u64 v[0:1], v[0:1], 0, s[16:17]
	v_lshlrev_b32_e32 v2, 1, v12
	v_lshl_add_u64 v[0:1], v[0:1], 0, v[2:3]
	global_store_dwordx4 v[0:1], v[4:7], off
	global_store_dwordx4 v[0:1], v[8:11], off offset:16
	s_barrier
; DI uint32_t pack2(float a, float b) { f2_t v = {a, b}; bf2_t r = __builtin_convertvector(v, bf2_t); return __builtin_bit_cast(uint32_t, r); }
; DI int opaque_tid() { int t = threadIdx.x; asm volatile("" : "+v"(t)); return t; }
; template <bool MAP>
; DI void transpose_tile(const float* __restrict__ src, int N, int K, int Nvalid, const float* __restrict__ g,
;                        u16* __restrict__ dst, int ldd, int k0, int n0, float* sT) {
;   const int tid = opaque_tid();
;   const int cg = (tid & 15) * 4, kq = tid >> 4;
;   const int sc = MAP ? src_col(n0 + cg) : ((n0 + cg < Nvalid) ? n0 + cg : -1);
; #pragma unroll
;   for (int i = 0; i < 4; ++i) {
;     const int kk = i * 16 + kq;
;     float4 v = make_float4(0.f, 0.f, 0.f, 0.f);
;     if (sc >= 0) {
;       v = *(const float4*)(src + (size_t)(k0 + kk) * N + sc);
;       if (g) { const float gg = g[k0 + kk]; v.x *= gg; v.y *= gg; v.z *= gg; v.w *= gg; }
;     }
;     float* d = sT + kk * 65 + cg;
;     d[0] = v.x; d[1] = v.y; d[2] = v.z; d[3] = v.w;
;   }
;   __syncthreads();
;   const int n = tid >> 2, kc = (tid & 3) * 16;
;   uint32_t o[8];
; #pragma unroll
;   for (int j = 0; j < 8; ++j) o[j] = pack2(sT[(kc + 2 * j) * 65 + n], sT[(kc + 2 * j + 1) * 65 + n]);
;   uint4* d = (uint4*)(dst + (size_t)(n0 + n) * ldd + k0 + kc);
;   d[0] = make_uint4(o[0], o[1], o[2], o[3]);
;   d[1] = make_uint4(o[4], o[5], o[6], o[7]);
;   __syncthreads();
; DI void convert_item(const Params& p, int layer, int item, float* sT) {
;     ...
;   if (item < CV_BR) {
;     int br = item >> 7, rem = item & 127, kt = rem & 7, nt = rem >> 3;
;     transpose_tile<false>(p.w_branch + ((size_t)layer * 3 + br) * 512 * 1024, 1024, 512, 1024, nullptr,
;                    (u16*)(wset + OFF_WT_BR) + (size_t)br * 1024 * LDB, LDB, kt * 64, nt * 64, sT);
;     return;
.LBB0_294:
	s_andn2_b64 vcc, exec, s[0:1]
	s_cbranch_vccnz .LBB0_296
	s_add_i32 s0, s59, 0xffffe450
	s_lshr_b32 s12, s0, 7
	v_readlane_b32 s0, v254, 44
	s_add_u32 s0, s0, s12
	v_readlane_b32 s1, v254, 43
	s_addc_u32 s1, s1, 0
	s_lshl_b64 s[0:1], s[0:1], 21
	s_add_u32 s14, s88, s0
	s_addc_u32 s15, s89, s1
	s_mul_hi_u32 s1, s12, 0x120000
	s_mul_i32 s12, s12, 0x120000
	v_readlane_b32 s0, v254, 45
	v_mov_b32_e32 v10, v128
	s_add_u32 s0, s0, s12
	v_readlane_b32 s12, v254, 46
	s_addc_u32 s1, s12, s1
	v_lshlrev_b32_e32 v0, 2, v10
	s_and_b32 s12, s58, 0x1c0
	s_and_b32 s13, s40, 0x3c0
	v_and_b32_e32 v6, 60, v0
	v_ashrrev_i32_e32 v7, 4, v10
	v_or_b32_e32 v0, s13, v6
	v_add_u32_e32 v8, s12, v7
	v_lshlrev_b32_e32 v2, 2, v0
	v_ashrrev_i32_e32 v9, 31, v8
	s_waitcnt lgkmcnt(0)
	v_lshl_add_u64 v[0:1], s[14:15], 0, v[2:3]
	v_lshlrev_b64 v[4:5], 12, v[8:9]
	s_movk_i32 s14, 0x104
	v_lshl_add_u64 v[4:5], v[0:1], 0, v[4:5]
	v_mul_lo_u32 v2, v7, s14
	v_lshl_add_u32 v2, v6, 2, v2
	v_add_co_u32_e32 v108, vcc, 0x10000, v4
	s_nop 1
	v_addc_co_u32_e32 v109, vcc, 0, v5, vcc
	v_add_co_u32_e32 v110, vcc, 0x20000, v4
	s_nop 1
	v_addc_co_u32_e32 v111, vcc, 0, v5, vcc
	v_add_co_u32_e32 v112, vcc, 0x30000, v4
	s_nop 1
	v_addc_co_u32_e32 v113, vcc, 0, v5, vcc
	global_load_dwordx4 v[4:7], v[4:5], off
	global_load_dwordx4 v[96:99], v[108:109], off
	global_load_dwordx4 v[100:103], v[110:111], off
	global_load_dwordx4 v[104:107], v[112:113], off
	v_add_u32_e32 v9, 0x1040, v2
	s_lshl_b32 s16, s12, 1
	s_waitcnt vmcnt(0)
	ds_write2_b32 v2, v4, v5 offset1:1
	ds_write2_b32 v2, v6, v7 offset0:2 offset1:3
	v_add_u32_e32 v4, 16, v8
	v_ashrrev_i32_e32 v5, 31, v4
	v_lshlrev_b64 v[4:5], 12, v[4:5]
	v_lshl_add_u64 v[4:5], v[0:1], 0, v[4:5]
	v_mov_b64_e32 v[4:5], v[96:97]
	v_mov_b64_e32 v[6:7], v[98:99]
	s_waitcnt vmcnt(0)
	ds_write2_b32 v9, v4, v5 offset1:1
	v_add_u32_e32 v4, 0x1048, v2
	ds_write2_b32 v4, v6, v7 offset1:1
	v_add_u32_e32 v4, 32, v8
	v_ashrrev_i32_e32 v5, 31, v4
	v_lshlrev_b64 v[4:5], 12, v[4:5]
	v_lshl_add_u64 v[4:5], v[0:1], 0, v[4:5]
	v_mov_b64_e32 v[4:5], v[100:101]
	v_mov_b64_e32 v[6:7], v[102:103]
	v_add_u32_e32 v9, 0x2080, v2
	s_waitcnt vmcnt(0)
	ds_write2_b32 v9, v4, v5 offset1:1
	v_add_u32_e32 v4, 0x2088, v2
	ds_write2_b32 v4, v6, v7 offset1:1
	v_add_u32_e32 v4, 48, v8
	v_ashrrev_i32_e32 v5, 31, v4
	v_lshlrev_b64 v[4:5], 12, v[4:5]
	v_lshl_add_u64 v[0:1], v[0:1], 0, v[4:5]
	v_mov_b64_e32 v[4:5], v[104:105]
	v_mov_b64_e32 v[6:7], v[106:107]
	v_add_u32_e32 v0, 0x30c8, v2
	v_add_u32_e32 v8, 0x30c0, v2
	v_ashrrev_i32_e32 v2, 2, v10
	v_add_u32_e32 v2, s13, v2
	s_waitcnt vmcnt(0)
	ds_write2_b32 v0, v6, v7 offset1:1
	v_lshlrev_b32_e32 v0, 4, v10
	v_and_b32_e32 v12, 48, v0
	v_and_b32_e32 v0, -4, v10
	v_mul_u32_u24_e32 v1, 0x41, v12
	v_lshl_add_u32 v10, v1, 2, v0
	ds_write2_b32 v8, v4, v5 offset1:1
	s_waitcnt lgkmcnt(0)
	s_barrier
	ds_read2_b32 v[0:1], v10 offset1:65
	v_add_u32_e32 v7, 0x400, v10
	v_add_u32_e32 v9, 0x800, v10
	v_add_u32_e32 v11, 0xc00, v10
	s_waitcnt lgkmcnt(0)
	v_cvt_pk_bf16_f32 v4, v0, v1
	ds_read2_b32 v[0:1], v10 offset0:130 offset1:195
	s_waitcnt lgkmcnt(0)
	v_cvt_pk_bf16_f32 v5, v0, v1
	ds_read2_b32 v[0:1], v7 offset0:4 offset1:69
	s_waitcnt lgkmcnt(0)
	v_cvt_pk_bf16_f32 v6, v0, v1
	ds_read2_b32 v[0:1], v7 offset0:134 offset1:199
	s_waitcnt lgkmcnt(0)
	v_cvt_pk_bf16_f32 v7, v0, v1
	ds_read2_b32 v[0:1], v9 offset0:8 offset1:73
	s_waitcnt lgkmcnt(0)
	v_cvt_pk_bf16_f32 v8, v0, v1
	ds_read2_b32 v[0:1], v9 offset0:138 offset1:203
	s_waitcnt lgkmcnt(0)
	v_cvt_pk_bf16_f32 v9, v0, v1
	ds_read2_b32 v[0:1], v11 offset0:12 offset1:77
	s_waitcnt lgkmcnt(0)
	v_cvt_pk_bf16_f32 v10, v0, v1
	ds_read2_b32 v[0:1], v11 offset0:142 offset1:207
	s_waitcnt lgkmcnt(0)
	v_cvt_pk_bf16_f32 v11, v0, v1
	v_mov_b64_e32 v[0:1], s[0:1]
	v_mad_i64_i32 v[0:1], s[0:1], v2, s4, v[0:1]
	v_lshl_add_u64 v[0:1], v[0:1], 0, s[16:17]
	v_lshlrev_b32_e32 v2, 1, v12
	v_lshl_add_u64 v[0:1], v[0:1], 0, v[2:3]
	global_store_dwordx4 v[0:1], v[4:7], off
	global_store_dwordx4 v[0:1], v[8:11], off offset:16
	s_barrier

; DI uint32_t pack2(float a, float b) { f2_t v = {a, b}; bf2_t r = __builtin_convertvector(v, bf2_t); return __builtin_bit_cast(uint32_t, r); }
; DI int opaque_tid() { int t = threadIdx.x; asm volatile("" : "+v"(t)); return t; }
; template <bool MAP>
; DI void transpose_tile(const float* __restrict__ src, int N, int K, int Nvalid, const float* __restrict__ g,
;                        u16* __restrict__ dst, int ldd, int k0, int n0, float* sT) {
;   const int tid = opaque_tid();
;   const int cg = (tid & 15) * 4, kq = tid >> 4;
;   const int sc = MAP ? src_col(n0 + cg) : ((n0 + cg < Nvalid) ? n0 + cg : -1);
; #pragma unroll
;   for (int i = 0; i < 4; ++i) {
;     const int kk = i * 16 + kq;
;     float4 v = make_float4(0.f, 0.f, 0.f, 0.f);
;     if (sc >= 0) {
;       v = *(const float4*)(src + (size_t)(k0 + kk) * N + sc);
;       if (g) { const float gg = g[k0 + kk]; v.x *= gg; v.y *= gg; v.z *= gg; v.w *= gg; }
;     }
;     float* d = sT + kk * 65 + cg;
;     d[0] = v.x; d[1] = v.y; d[2] = v.z; d[3] = v.w;
;   }
;   __syncthreads();
;   const int n = tid >> 2, kc = (tid & 3) * 16;
;   uint32_t o[8];
; #pragma unroll
;   for (int j = 0; j < 8; ++j) o[j] = pack2(sT[(kc + 2 * j) * 65 + n], sT[(kc + 2 * j + 1) * 65 + n]);
;   uint4* d = (uint4*)(dst + (size_t)(n0 + n) * ldd + k0 + kc);
;   d[0] = make_uint4(o[0], o[1], o[2], o[3]);
;   d[1] = make_uint4(o[4], o[5], o[6], o[7]);
;   __syncthreads();
; DI void convert_item(const Params& p, int layer, int item, float* sT) {
;     ...
;   {
;     int kt = item & 15, nt = item >> 4;
;     transpose_tile<false>(p.w_out + (size_t)layer * 1024 * 1024, 1024, 1024, 1024, nullptr, (u16*)(wset + OFF_WT_OUT), LDX, kt * 64, nt * 64, sT);
;   }
.LBB0_1489:
	s_cmpk_gt_i32 s18, 0x75f
	s_mov_b64 s[0:1], -1
	s_cbranch_scc0 .LBB0_1519
	s_cmpk_gt_u32 s18, 0x78f
	s_cbranch_scc0 .LBB0_1508
	s_cmpk_gt_u32 s18, 0x7af
	s_cbranch_scc0 .LBB0_1497
	s_cmpk_gt_u32 s18, 0x92f
	s_cbranch_scc0 .LBB0_1494
	v_mov_b32_e32 v10, v128
	s_and_b32 s0, s15, 0x3c0
	s_and_b32 s1, s14, 0x7fffffc0
	s_addk_i32 s1, 0xdb40
	v_lshlrev_b32_e32 v0, 2, v10
	v_ashrrev_i32_e32 v7, 4, v10
	v_and_b32_e32 v6, 60, v0
	v_add_u32_e32 v8, s0, v7
	v_or_b32_e32 v2, s1, v6
	v_ashrrev_i32_e32 v9, 31, v8
	s_waitcnt lgkmcnt(0)
	v_lshl_add_u64 v[0:1], v[2:3], 2, s[90:91]
	v_lshlrev_b64 v[4:5], 12, v[8:9]
	s_movk_i32 s6, 0x104
	v_lshl_add_u64 v[4:5], v[0:1], 0, v[4:5]
	v_mul_lo_u32 v2, v7, s6
	v_lshl_add_u32 v2, v6, 2, v2
	v_add_co_u32_e32 v108, vcc, 0x10000, v4
	s_nop 1
	v_addc_co_u32_e32 v109, vcc, 0, v5, vcc
	v_add_co_u32_e32 v110, vcc, 0x20000, v4
	s_nop 1
	v_addc_co_u32_e32 v111, vcc, 0, v5, vcc
	v_add_co_u32_e32 v112, vcc, 0x30000, v4
	s_nop 1
	v_addc_co_u32_e32 v113, vcc, 0, v5, vcc
	global_load_dwordx4 v[4:7], v[4:5], off
	global_load_dwordx4 v[96:99], v[108:109], off
	global_load_dwordx4 v[100:103], v[110:111], off
	global_load_dwordx4 v[104:107], v[112:113], off
	v_add_u32_e32 v9, 0x1040, v2
	v_readlane_b32 s6, v252, 50
	v_readlane_b32 s7, v252, 51
	s_lshl_b32 s16, s0, 1
	s_waitcnt vmcnt(0)
	ds_write2_b32 v2, v4, v5 offset1:1
	ds_write2_b32 v2, v6, v7 offset0:2 offset1:3
	v_add_u32_e32 v4, 16, v8
	v_ashrrev_i32_e32 v5, 31, v4
	v_lshlrev_b64 v[4:5], 12, v[4:5]
	v_lshl_add_u64 v[4:5], v[0:1], 0, v[4:5]
	v_mov_b64_e32 v[4:5], v[96:97]
	v_mov_b64_e32 v[6:7], v[98:99]
	s_waitcnt vmcnt(0)
	ds_write2_b32 v9, v4, v5 offset1:1
	v_add_u32_e32 v4, 0x1048, v2
	ds_write2_b32 v4, v6, v7 offset1:1
	v_add_u32_e32 v4, 32, v8
	v_ashrrev_i32_e32 v5, 31, v4
	v_lshlrev_b64 v[4:5], 12, v[4:5]
	v_lshl_add_u64 v[4:5], v[0:1], 0, v[4:5]
	v_mov_b64_e32 v[4:5], v[100:101]
	v_mov_b64_e32 v[6:7], v[102:103]
	v_add_u32_e32 v9, 0x2080, v2
	s_waitcnt vmcnt(0)
	ds_write2_b32 v9, v4, v5 offset1:1
	v_add_u32_e32 v4, 0x2088, v2
	ds_write2_b32 v4, v6, v7 offset1:1
	v_add_u32_e32 v4, 48, v8
	v_ashrrev_i32_e32 v5, 31, v4
	v_lshlrev_b64 v[4:5], 12, v[4:5]
	v_lshl_add_u64 v[0:1], v[0:1], 0, v[4:5]
	v_mov_b64_e32 v[4:5], v[104:105]
	v_mov_b64_e32 v[6:7], v[106:107]
	v_add_u32_e32 v0, 0x30c8, v2
	v_add_u32_e32 v8, 0x30c0, v2
	v_ashrrev_i32_e32 v2, 2, v10
	v_add_u32_e32 v2, s1, v2
	s_mov_b64 s[0:1], 0
	s_waitcnt vmcnt(0)
	ds_write2_b32 v0, v6, v7 offset1:1
	v_lshlrev_b32_e32 v0, 4, v10
	v_and_b32_e32 v12, 48, v0
	v_and_b32_e32 v0, -4, v10
	v_mul_u32_u24_e32 v1, 0x41, v12
	v_lshl_add_u32 v10, v1, 2, v0
	ds_write2_b32 v8, v4, v5 offset1:1
	s_waitcnt lgkmcnt(0)
	s_barrier
	ds_read2_b32 v[0:1], v10 offset1:65
	v_add_u32_e32 v7, 0x400, v10
	v_add_u32_e32 v9, 0x800, v10
	v_add_u32_e32 v11, 0xc00, v10
	s_waitcnt lgkmcnt(0)
	v_cvt_pk_bf16_f32 v4, v0, v1
	ds_read2_b32 v[0:1], v10 offset0:130 offset1:195
	s_waitcnt lgkmcnt(0)
	v_cvt_pk_bf16_f32 v5, v0, v1
	ds_read2_b32 v[0:1], v7 offset0:4 offset1:69
	s_waitcnt lgkmcnt(0)
	v_cvt_pk_bf16_f32 v6, v0, v1
	ds_read2_b32 v[0:1], v7 offset0:134 offset1:199
	s_waitcnt lgkmcnt(0)
	v_cvt_pk_bf16_f32 v7, v0, v1
	ds_read2_b32 v[0:1], v9 offset0:8 offset1:73
	s_waitcnt lgkmcnt(0)
	v_cvt_pk_bf16_f32 v8, v0, v1
	ds_read2_b32 v[0:1], v9 offset0:138 offset1:203
	s_waitcnt lgkmcnt(0)
	v_cvt_pk_bf16_f32 v9, v0, v1
	ds_read2_b32 v[0:1], v11 offset0:12 offset1:77
	s_waitcnt lgkmcnt(0)
	v_cvt_pk_bf16_f32 v10, v0, v1
	ds_read2_b32 v[0:1], v11 offset0:142 offset1:207
	s_waitcnt lgkmcnt(0)
	v_cvt_pk_bf16_f32 v11, v0, v1
	v_mov_b64_e32 v[0:1], s[6:7]
	v_mad_i64_i32 v[0:1], s[6:7], v2, s24, v[0:1]
	v_lshl_add_u64 v[0:1], v[0:1], 0, s[16:17]
	v_lshlrev_b32_e32 v2, 1, v12
	v_lshl_add_u64 v[0:1], v[0:1], 0, v[2:3]
	global_store_dwordx4 v[0:1], v[4:7], off
	global_store_dwordx4 v[0:1], v[8:11], off offset:16
	s_barrier
; DI uint32_t pack2(float a, float b) { f2_t v = {a, b}; bf2_t r = __builtin_convertvector(v, bf2_t); return __builtin_bit_cast(uint32_t, r); }
; DI int opaque_tid() { int t = threadIdx.x; asm volatile("" : "+v"(t)); return t; }
; template <bool MAP>
; DI void transpose_tile(const float* __restrict__ src, int N, int K, int Nvalid, const float* __restrict__ g,
;                        u16* __restrict__ dst, int ldd, int k0, int n0, float* sT) {
;   const int tid = opaque_tid();
;   const int cg = (tid & 15) * 4, kq = tid >> 4;
;   const int sc = MAP ? src_col(n0 + cg) : ((n0 + cg < Nvalid) ? n0 + cg : -1);
; #pragma unroll
;   for (int i = 0; i < 4; ++i) {
;     const int kk = i * 16 + kq;
;     float4 v = make_float4(0.f, 0.f, 0.f, 0.f);
;     if (sc >= 0) {
;       v = *(const float4*)(src + (size_t)(k0 + kk) * N + sc);
;       if (g) { const float gg = g[k0 + kk]; v.x *= gg; v.y *= gg; v.z *= gg; v.w *= gg; }
;     }
;     float* d = sT + kk * 65 + cg;
;     d[0] = v.x; d[1] = v.y; d[2] = v.z; d[3] = v.w;
;   }
;   __syncthreads();
;   const int n = tid >> 2, kc = (tid & 3) * 16;
;   uint32_t o[8];
; #pragma unroll
;   for (int j = 0; j < 8; ++j) o[j] = pack2(sT[(kc + 2 * j) * 65 + n], sT[(kc + 2 * j + 1) * 65 + n]);
;   uint4* d = (uint4*)(dst + (size_t)(n0 + n) * ldd + k0 + kc);
;   d[0] = make_uint4(o[0], o[1], o[2], o[3]);
;   d[1] = make_uint4(o[4], o[5], o[6], o[7]);
;   __syncthreads();
; DI void convert_item(const Params& p, int layer, int item, float* sT) {
;     ...
;   if (item < CV_BR) {
;     int br = item >> 7, rem = item & 127, kt = rem & 7, nt = rem >> 3;
;     transpose_tile<false>(p.w_branch + ((size_t)layer * 3 + br) * 512 * 1024, 1024, 512, 1024, nullptr,
;                    (u16*)(wset + OFF_WT_BR) + (size_t)br * 1024 * LDB, LDB, kt * 64, nt * 64, sT);
;     return;
.LBB0_1494:
	s_andn2_b64 vcc, exec, s[0:1]
	s_cbranch_vccnz .LBB0_1496
	s_add_i32 s0, s18, 0xfffff850
	s_lshr_b32 s16, s0, 7
	s_lshl_b64 s[0:1], s[16:17], 21
	s_add_u32 s10, s88, s0
	s_addc_u32 s11, s89, s1
	s_mul_i32 s0, s16, 0x120000
	v_readlane_b32 s6, v252, 52
	v_mov_b32_e32 v10, v128
	s_mul_hi_u32 s1, s16, 0x120000
	s_add_u32 s0, s6, s0
	v_readlane_b32 s6, v252, 53
	s_addc_u32 s1, s6, s1
	v_lshlrev_b32_e32 v0, 2, v10
	s_and_b32 s6, s15, 0x1c0
	s_and_b32 s7, s13, 0x3c0
	v_and_b32_e32 v6, 60, v0
	v_ashrrev_i32_e32 v7, 4, v10
	v_or_b32_e32 v0, s7, v6
	v_add_u32_e32 v8, s6, v7
	v_lshlrev_b32_e32 v2, 2, v0
	v_ashrrev_i32_e32 v9, 31, v8
	s_waitcnt lgkmcnt(0)
	v_lshl_add_u64 v[0:1], s[10:11], 0, v[2:3]
	v_lshlrev_b64 v[4:5], 12, v[8:9]
	s_movk_i32 s10, 0x104
	v_lshl_add_u64 v[4:5], v[0:1], 0, v[4:5]
	v_mul_lo_u32 v2, v7, s10
	v_lshl_add_u32 v2, v6, 2, v2
	v_add_co_u32_e32 v108, vcc, 0x10000, v4
	s_nop 1
	v_addc_co_u32_e32 v109, vcc, 0, v5, vcc
	v_add_co_u32_e32 v110, vcc, 0x20000, v4
	s_nop 1
	v_addc_co_u32_e32 v111, vcc, 0, v5, vcc
	v_add_co_u32_e32 v112, vcc, 0x30000, v4
	s_nop 1
	v_addc_co_u32_e32 v113, vcc, 0, v5, vcc
	global_load_dwordx4 v[4:7], v[4:5], off
	global_load_dwordx4 v[96:99], v[108:109], off
	global_load_dwordx4 v[100:103], v[110:111], off
	global_load_dwordx4 v[104:107], v[112:113], off
	v_add_u32_e32 v9, 0x1040, v2
	s_lshl_b32 s16, s6, 1
	s_waitcnt vmcnt(0)
	ds_write2_b32 v2, v4, v5 offset1:1
	ds_write2_b32 v2, v6, v7 offset0:2 offset1:3
	v_add_u32_e32 v4, 16, v8
	v_ashrrev_i32_e32 v5, 31, v4
	v_lshlrev_b64 v[4:5], 12, v[4:5]
	v_lshl_add_u64 v[4:5], v[0:1], 0, v[4:5]
	v_mov_b64_e32 v[4:5], v[96:97]
	v_mov_b64_e32 v[6:7], v[98:99]
	s_waitcnt vmcnt(0)
	ds_write2_b32 v9, v4, v5 offset1:1
	v_add_u32_e32 v4, 0x1048, v2
	ds_write2_b32 v4, v6, v7 offset1:1
	v_add_u32_e32 v4, 32, v8
	v_ashrrev_i32_e32 v5, 31, v4
	v_lshlrev_b64 v[4:5], 12, v[4:5]
	v_lshl_add_u64 v[4:5], v[0:1], 0, v[4:5]
	v_mov_b64_e32 v[4:5], v[100:101]
	v_mov_b64_e32 v[6:7], v[102:103]
	v_add_u32_e32 v9, 0x2080, v2
	s_waitcnt vmcnt(0)
	ds_write2_b32 v9, v4, v5 offset1:1
	v_add_u32_e32 v4, 0x2088, v2
	ds_write2_b32 v4, v6, v7 offset1:1
	v_add_u32_e32 v4, 48, v8
	v_ashrrev_i32_e32 v5, 31, v4
	v_lshlrev_b64 v[4:5], 12, v[4:5]
	v_lshl_add_u64 v[0:1], v[0:1], 0, v[4:5]
	v_mov_b64_e32 v[4:5], v[104:105]
	v_mov_b64_e32 v[6:7], v[106:107]
	v_add_u32_e32 v0, 0x30c8, v2
	v_add_u32_e32 v8, 0x30c0, v2
	v_ashrrev_i32_e32 v2, 2, v10
	v_add_u32_e32 v2, s7, v2
	s_waitcnt vmcnt(0)
	ds_write2_b32 v0, v6, v7 offset1:1
	v_lshlrev_b32_e32 v0, 4, v10
	v_and_b32_e32 v12, 48, v0
	v_and_b32_e32 v0, -4, v10
	v_mul_u32_u24_e32 v1, 0x41, v12
	v_lshl_add_u32 v10, v1, 2, v0
	ds_write2_b32 v8, v4, v5 offset1:1
	s_waitcnt lgkmcnt(0)
	s_barrier
	ds_read2_b32 v[0:1], v10 offset1:65
	v_add_u32_e32 v7, 0x400, v10
	v_add_u32_e32 v9, 0x800, v10
	v_add_u32_e32 v11, 0xc00, v10
	s_waitcnt lgkmcnt(0)
	v_cvt_pk_bf16_f32 v4, v0, v1
	ds_read2_b32 v[0:1], v10 offset0:130 offset1:195
	s_waitcnt lgkmcnt(0)
	v_cvt_pk_bf16_f32 v5, v0, v1
	ds_read2_b32 v[0:1], v7 offset0:4 offset1:69
	s_waitcnt lgkmcnt(0)
	v_cvt_pk_bf16_f32 v6, v0, v1
	ds_read2_b32 v[0:1], v7 offset0:134 offset1:199
	s_waitcnt lgkmcnt(0)
	v_cvt_pk_bf16_f32 v7, v0, v1
	ds_read2_b32 v[0:1], v9 offset0:8 offset1:73
	s_waitcnt lgkmcnt(0)
	v_cvt_pk_bf16_f32 v8, v0, v1
	ds_read2_b32 v[0:1], v9 offset0:138 offset1:203
	s_waitcnt lgkmcnt(0)
	v_cvt_pk_bf16_f32 v9, v0, v1
	ds_read2_b32 v[0:1], v11 offset0:12 offset1:77
	s_waitcnt lgkmcnt(0)
	v_cvt_pk_bf16_f32 v10, v0, v1
	ds_read2_b32 v[0:1], v11 offset0:142 offset1:207
	s_waitcnt lgkmcnt(0)
	v_cvt_pk_bf16_f32 v11, v0, v1
	v_mov_b64_e32 v[0:1], s[0:1]
	v_mad_i64_i32 v[0:1], s[0:1], v2, s4, v[0:1]
	v_lshl_add_u64 v[0:1], v[0:1], 0, s[16:17]
	v_lshlrev_b32_e32 v2, 1, v12
	v_lshl_add_u64 v[0:1], v[0:1], 0, v[2:3]
	global_store_dwordx4 v[0:1], v[4:7], off
	global_store_dwordx4 v[0:1], v[8:11], off offset:16
	s_barrier
